# GLA output store addressed through an SGPR base plus a 32-bit VGPR offset (no 64-bit address math per store)
# baseline (speedup 1.0000x reference)
.LBB0_231:
	s_or_b64 exec, exec, s[4:5]
	v_lshlrev_b32_e32 v34, 6, v42
	s_waitcnt vmcnt(5)
	ds_write_b128 v114, v[26:29]
	s_waitcnt vmcnt(2)
	ds_write_b128 v111, v[30:33] offset:36864
	v_lshlrev_b32_e32 v26, 1, v34
	v_mov_b32_e32 v27, v69
	v_lshl_add_u64 v[28:29], v[72:73], 0, v[26:27]
	v_lshl_add_u64 v[30:31], v[76:77], 0, v[26:27]
	global_load_dwordx4 v[34:37], v[28:29], off
	global_load_dwordx4 v[38:41], v[30:31], off
	v_cndmask_b32_e64 v28, v91, v90, s[0:1]
	v_lshlrev_b32_e32 v28, 7, v28
	v_mov_b32_e32 v29, v69
	v_lshl_add_u64 v[26:27], v[78:79], 0, v[26:27]
	v_lshl_add_u64 v[30:31], v[74:75], 0, v[28:29]
	global_load_dwordx4 v[26:29], v[26:27], off
	s_nop 0
	global_load_dwordx4 v[30:33], v[30:31], off
	s_waitcnt lgkmcnt(0)
	s_barrier
	ds_read_b128 v[42:45], v95 offset:55296
	v_add_u32_e32 v125, v92, v93
	ds_read_b128 v[46:49], v125
	ds_read_b128 v[54:57], v125 offset:64
	ds_read_b128 v[50:53], v95 offset:55360
	ds_read_b128 v[128:131], v95 offset:57600
	ds_read_b128 v[132:135], v95 offset:57664
	s_waitcnt lgkmcnt(4)
	v_mfma_f32_16x16x32_bf16 v[42:45], v[42:45], v[46:49], 0
	ds_read_b128 v[136:139], v95 offset:27648
	ds_read_b128 v[140:143], v95 offset:27712
	ds_read_b128 v[144:147], v95 offset:29952
	ds_read_b128 v[150:153], v95 offset:30016
	s_and_b64 s[4:5], s[0:1], exec
	s_waitcnt lgkmcnt(5)
	v_mfma_f32_16x16x32_bf16 v[128:131], v[128:131], v[46:49], 0
	s_cselect_b32 s5, s41, s39
	s_cselect_b32 s4, s40, s38
	s_lshl_b32 s30, s26, 12
	v_mfma_f32_16x16x32_bf16 v[42:45], v[50:53], v[54:57], v[42:45]
	s_lshl_b32 s10, s28, 7
	s_lshl_b32 s26, s28, 8
	s_add_u32 s26, s4, s26
	s_waitcnt lgkmcnt(4)
	v_mfma_f32_16x16x32_bf16 v[128:131], v[132:135], v[54:57], v[128:131]
	s_addc_u32 s27, s5, 0
	s_nop 1
	v_pk_mul_f32 v[44:45], v[60:61], v[44:45]
	v_pk_mul_f32 v[42:43], v[58:59], v[42:43]
	s_waitcnt lgkmcnt(3)
	v_mfma_f32_16x16x32_bf16 v[136:139], v[136:139], v[46:49], 0
	v_cvt_pk_bf16_f32 v42, v42, v43
	v_pk_mul_f32 v[80:81], v[64:65], v[130:131]
	v_pk_mul_f32 v[128:129], v[62:63], v[128:129]
	s_waitcnt lgkmcnt(1)
	v_mfma_f32_16x16x32_bf16 v[46:49], v[144:147], v[46:49], 0
	v_cvt_pk_bf16_f32 v43, v44, v45
	ds_write_b64 v115, v[42:43] offset:18432
	v_cvt_pk_bf16_f32 v42, v128, v129
	v_cvt_pk_bf16_f32 v43, v80, v81
	ds_write_b64 v116, v[42:43] offset:18432
	ds_read_b64_tr_b16 v[44:45], v112 offset:37440
	ds_read_b64_tr_b16 v[42:43], v112 offset:36864
	v_mfma_f32_16x16x32_bf16 v[50:53], v[140:143], v[54:57], v[136:139]
	s_lshl_b32 s28, s31, 6
	s_lshl_b32 s31, s31, 7
	s_add_u32 s26, s26, s31
	s_waitcnt lgkmcnt(4)
	v_mfma_f32_16x16x32_bf16 v[54:57], v[150:153], v[54:57], v[46:49]
	s_nop 2
	ds_read_b64_tr_b16 v[48:49], v112 offset:37472
	ds_read_b64_tr_b16 v[46:47], v112 offset:36896
	ds_read_b64_tr_b16 v[128:129], v112 offset:41472
	ds_read_b64_tr_b16 v[130:131], v112 offset:42048
	ds_read_b64_tr_b16 v[134:135], v112 offset:42080
	ds_read_b64_tr_b16 v[132:133], v112 offset:41504
	s_waitcnt lgkmcnt(6)
	v_mfma_f32_16x16x32_bf16 v[42:45], v[42:45], v[2:5], 0
	s_addc_u32 s27, s27, 0
	v_add_u32_e32 v127, v96, v87
	s_add_u32 s26, s26, s24
	s_waitcnt lgkmcnt(4)
	v_mfma_f32_16x16x32_bf16 v[46:49], v[46:49], v[2:5], 0
	s_addc_u32 s27, s27, 0
	s_mov_b32 s29, 0
	v_lshl_add_u64 v[80:81], v[170:171], 1, s[26:27]
	s_mov_b64 s[6:7], s[26:27]
	v_lshlrev_b32_e32 v176, 1, v170
	s_waitcnt lgkmcnt(2)
	v_mfma_f32_16x16x32_bf16 v[42:45], v[128:131], v[6:9], v[42:45]
	v_add_u32_e32 v128, v96, v88
	s_mov_b32 s31, -1
	v_mov_b32_e32 v129, v110
	s_waitcnt lgkmcnt(0)
	v_mfma_f32_16x16x32_bf16 v[46:49], v[132:135], v[6:9], v[46:49]
	v_mov_b32_e32 v130, v91
	s_nop 1
	ds_write_b128 v127, v[42:45]
	v_mov_b32_e32 v42, 0
	v_mov_b32_e32 v43, v42
	v_mov_b32_e32 v44, v42
	s_nop 0
	ds_write_b128 v128, v[46:49]
	v_mov_b32_e32 v45, v42
	v_mov_b32_e32 v46, v42
	v_mov_b32_e32 v47, v42
	v_mov_b32_e32 v48, v42
	v_mov_b32_e32 v49, v42
	s_waitcnt lgkmcnt(0)
	s_barrier
	s_branch .LBB0_233

.LBB0_233:
	ds_read_b64_tr_b16 v[134:135], v117 offset:576
	ds_read_b64_tr_b16 v[132:133], v117
	ds_read_b128 v[136:139], v125 offset:18432
	ds_read_b64_tr_b16 v[142:143], v117 offset:608
	ds_read_b64_tr_b16 v[140:141], v117 offset:32
	ds_read_b128 v[144:147], v125 offset:18496
	ds_read_b64_tr_b16 v[150:151], v117 offset:4608
	ds_read_b64_tr_b16 v[152:153], v117 offset:5184
	ds_read_b64_tr_b16 v[156:157], v117 offset:5216
	ds_read_b64_tr_b16 v[154:155], v117 offset:4640
	s_waitcnt lgkmcnt(7)
	v_mfma_f32_16x16x32_bf16 v[50:53], v[132:135], v[136:139], v[50:53]
	ds_read_b64_tr_b16 v[158:159], v101 offset:55296
	ds_read_b64_tr_b16 v[160:161], v101 offset:55872
	v_add_u32_e32 v131, v94, v97
	s_waitcnt lgkmcnt(7)
	v_mfma_f32_16x16x32_bf16 v[136:139], v[140:143], v[136:139], v[54:57]
	s_waitcnt lgkmcnt(4)
	v_mfma_f32_16x16x32_bf16 v[50:53], v[150:153], v[144:147], v[50:53]
	s_nop 0
	v_add_u32_e32 v56, s29, v71
	v_add_u32_e32 v54, 64, v129
	v_cndmask_b32_e64 v54, v54, v56, s[0:1]
	s_waitcnt lgkmcnt(2)
	v_mfma_f32_16x16x32_bf16 v[136:139], v[154:157], v[144:147], v[136:139]
	ds_read_b64_tr_b16 v[144:145], v101 offset:59904
	ds_read_b64_tr_b16 v[146:147], v101 offset:60480
	v_add_u32_e32 v54, s30, v54
	s_nop 0
	s_waitcnt lgkmcnt(2)
	v_mfma_f32_16x16x32_bf16 v[46:49], v[158:161], v[132:135], v[46:49]
	v_cvt_pk_bf16_f32 v172, v50, v51
	v_cvt_pk_bf16_f32 v173, v52, v53
	ds_read_b128 v[50:53], v118 offset:46080
	v_mfma_f32_16x16x32_bf16 v[42:45], v[158:161], v[140:143], v[42:45]
	v_lshl_add_u32 v54, v54, 10, v176
	s_nop 0
	s_nop 0
	s_waitcnt lgkmcnt(1)
	v_mfma_f32_16x16x32_bf16 v[46:49], v[144:147], v[150:153], v[46:49]
	v_cvt_pk_bf16_f32 v174, v136, v137
	v_cvt_pk_bf16_f32 v175, v138, v139
	s_nop 1
	v_permlane16_swap_b32_e32 v172, v174
	v_permlane16_swap_b32_e32 v173, v175
	global_store_dwordx4 v54, v[172:175], s[6:7]
	v_mfma_f32_16x16x32_bf16 v[42:45], v[144:147], v[154:157], v[42:45]
	s_waitcnt vmcnt(8)
	v_lshlrev_b32_e32 v136, 16, v22
	s_waitcnt lgkmcnt(0)
	s_nop 0
	v_pk_mul_f32 v[48:49], v[52:53], v[48:49]
	v_pk_mul_f32 v[46:47], v[50:51], v[46:47]
	v_and_b32_e32 v137, 0xffff0000, v22
	v_lshlrev_b32_e32 v22, 16, v23
	v_pk_mul_f32 v[44:45], v[52:53], v[44:45]
	v_pk_mul_f32 v[42:43], v[50:51], v[42:43]
	v_cvt_pk_bf16_f32 v50, v46, v47
	v_cvt_pk_bf16_f32 v51, v48, v49
	ds_write_b64 v131, v[50:51] offset:27648
	v_cvt_pk_bf16_f32 v50, v42, v43
	v_cvt_pk_bf16_f32 v51, v44, v45
	ds_write_b64 v119, v[50:51] offset:27648
	ds_read_b128 v[50:53], v120
	ds_read_b128 v[132:135], v120 offset:16
	v_and_b32_e32 v23, 0xffff0000, v23
	v_lshlrev_b32_e32 v138, 16, v24
	v_and_b32_e32 v139, 0xffff0000, v24
	s_waitcnt lgkmcnt(1)
	v_exp_f32_e64 v54, -v50
	v_exp_f32_e64 v55, -v51
	v_exp_f32_e32 v50, v50
	v_exp_f32_e32 v51, v51
	s_waitcnt lgkmcnt(0)
	v_exp_f32_e32 v24, v134
	v_pk_mul_f32 v[54:55], v[54:55], v[136:137]
	s_waitcnt vmcnt(6)
	v_lshlrev_b32_e32 v136, 16, v18
	v_and_b32_e32 v137, 0xffff0000, v18
	v_pk_mul_f32 v[136:137], v[50:51], v[136:137]
	s_nop 0
	v_cvt_pk_bf16_f32 v18, v136, v137
	v_cvt_pk_bf16_f32 v136, v54, v55
	v_exp_f32_e64 v54, -v52
	v_exp_f32_e64 v55, -v53
	v_exp_f32_e32 v52, v52
	v_exp_f32_e32 v53, v53
	v_pk_mul_f32 v[22:23], v[54:55], v[22:23]
	v_lshlrev_b32_e32 v54, 16, v19
	v_and_b32_e32 v55, 0xffff0000, v19
	v_pk_mul_f32 v[54:55], v[52:53], v[54:55]
	v_cvt_pk_bf16_f32 v137, v22, v23
	v_cvt_pk_bf16_f32 v19, v54, v55
	v_exp_f32_e64 v54, -v132
	v_exp_f32_e64 v55, -v133
	v_exp_f32_e32 v22, v132
	v_exp_f32_e32 v23, v133
	v_lshlrev_b32_e32 v132, 16, v20
	v_pk_mul_f32 v[54:55], v[54:55], v[138:139]
	v_and_b32_e32 v133, 0xffff0000, v20
	v_pk_mul_f32 v[132:133], v[22:23], v[132:133]
	v_cvt_pk_bf16_f32 v138, v54, v55
	v_exp_f32_e64 v54, -v134
	v_exp_f32_e64 v55, -v135
	v_cvt_pk_bf16_f32 v20, v132, v133
	v_lshlrev_b32_e32 v132, 16, v25
	v_and_b32_e32 v133, 0xffff0000, v25
	v_exp_f32_e32 v25, v135
	v_pk_mul_f32 v[54:55], v[54:55], v[132:133]
	v_lshlrev_b32_e32 v132, 16, v21
	v_and_b32_e32 v133, 0xffff0000, v21
	v_pk_mul_f32 v[132:133], v[24:25], v[132:133]
	v_cvt_pk_bf16_f32 v139, v54, v55
	v_cvt_pk_bf16_f32 v21, v132, v133
	ds_write_b128 v111, v[18:21]
	ds_write_b128 v111, v[136:139] offset:64512
	s_and_saveexec_b64 s[26:27], vcc
	s_cbranch_execz .LBB0_235
	ds_write_b128 v126, v[50:53] offset:46336
	ds_write_b128 v126, v[22:25] offset:46352
.LBB0_235:
	s_or_b64 exec, exec, s[26:27]
	ds_write_b128 v121, v[10:13]
	s_waitcnt vmcnt(5)
	ds_write_b128 v111, v[14:17] offset:36864
	v_add_u32_e32 v10, s29, v90
	v_cndmask_b32_e64 v10, v130, v10, s[0:1]
	s_add_i32 s31, s31, 2
	v_lshl_add_u32 v14, v10, 7, v68
	s_min_u32 s26, s31, 60
	global_load_dwordx4 v[18:21], v14, s[94:95]
	global_load_dwordx4 v[22:25], v14, s[96:97]
	v_lshl_add_u32 v12, s26, 6, v90
	v_sub_u32_e32 v13, 0xfff, v12
	v_cndmask_b32_e64 v12, v13, v12, s[0:1]
	v_lshl_add_u32 v54, v12, 7, v68
	global_load_dwordx4 v[10:13], v14, s[98:99]
	s_nop 0
	global_load_dwordx4 v[14:17], v54, s[100:101]
	s_waitcnt lgkmcnt(0)
	s_barrier
	ds_read_b128 v[50:53], v95 offset:64512
	ds_read_b128 v[132:135], v125
	ds_read_b128 v[136:139], v125 offset:64
	ds_read_b128 v[140:143], v95 offset:64576
	ds_read_b128 v[144:147], v102 offset:2304
	ds_read_b128 v[150:153], v102 offset:2368
	s_waitcnt lgkmcnt(4)
	v_mfma_f32_16x16x32_bf16 v[50:53], v[50:53], v[132:135], 0
	ds_read_b128 v[154:157], v95 offset:27648
	ds_read_b128 v[158:161], v95 offset:27712
	ds_read_b128 v[162:165], v95 offset:29952
	ds_read_b128 v[166:169], v95 offset:30016
	s_waitcnt lgkmcnt(5)
	v_mfma_f32_16x16x32_bf16 v[144:147], v[144:147], v[132:135], 0
	v_mfma_f32_16x16x32_bf16 v[50:53], v[140:143], v[136:139], v[50:53]
	s_waitcnt lgkmcnt(4)
	v_mfma_f32_16x16x32_bf16 v[140:143], v[150:153], v[136:139], v[144:147]
	s_waitcnt lgkmcnt(3)
	v_mfma_f32_16x16x32_bf16 v[154:157], v[154:157], v[132:135], 0
	s_nop 3
	v_mul_f32_e64 v52, v60, v52
	v_mul_f32_e64 v53, v61, v53
	v_pk_mul_f32 v[50:51], v[58:59], v[50:51]
	v_pk_mul_f32 v[142:143], v[64:65], v[142:143]
	s_waitcnt lgkmcnt(1)
	v_mfma_f32_16x16x32_bf16 v[132:135], v[162:165], v[132:135], 0
	v_mul_f32_e64 v140, v62, v140
	v_mul_f32_e64 v141, v63, v141
	v_cvt_pk_bf16_f32 v50, v50, v51
	v_cvt_pk_bf16_f32 v51, v52, v53
	ds_write_b64 v115, v[50:51] offset:18432
	v_cvt_pk_bf16_f32 v50, v140, v141
	v_cvt_pk_bf16_f32 v51, v142, v143
	ds_write_b64 v116, v[50:51] offset:18432
	ds_read_b64_tr_b16 v[52:53], v112 offset:37440
	ds_read_b64_tr_b16 v[50:51], v112 offset:36864
	v_mfma_f32_16x16x32_bf16 v[144:147], v[158:161], v[136:139], v[154:157]
	s_waitcnt lgkmcnt(4)
	v_mfma_f32_16x16x32_bf16 v[132:135], v[166:169], v[136:139], v[132:135]
	ds_read_b64_tr_b16 v[138:139], v112 offset:37472
	ds_read_b64_tr_b16 v[136:137], v112 offset:36896
	ds_read_b64_tr_b16 v[140:141], v112 offset:41472
	ds_read_b64_tr_b16 v[142:143], v112 offset:42048
	ds_read_b64_tr_b16 v[152:153], v112 offset:42080
	ds_read_b64_tr_b16 v[150:151], v112 offset:41504
	s_waitcnt lgkmcnt(6)
	v_mfma_f32_16x16x32_bf16 v[50:53], v[50:53], v[2:5], 0
	s_waitcnt lgkmcnt(4)
	v_mfma_f32_16x16x32_bf16 v[136:139], v[136:139], v[2:5], 0
	s_waitcnt lgkmcnt(2)
	v_mfma_f32_16x16x32_bf16 v[50:53], v[140:143], v[6:9], v[50:53]
	s_waitcnt lgkmcnt(0)
	v_mfma_f32_16x16x32_bf16 v[136:139], v[150:153], v[6:9], v[136:139]
	s_nop 5
	ds_write_b128 v123, v[50:53]
	s_nop 0
	ds_write_b128 v124, v[136:139]
	s_waitcnt lgkmcnt(0)
	s_barrier
	ds_read_b64_tr_b16 v[50:51], v122
	ds_read_b64_tr_b16 v[52:53], v122 offset:576
	ds_read_b64_tr_b16 v[138:139], v122 offset:608
	ds_read_b64_tr_b16 v[140:141], v122 offset:4608
	ds_read_b64_tr_b16 v[136:137], v122 offset:32
	ds_read_b128 v[150:153], v125 offset:18432
	ds_read_b128 v[154:157], v125 offset:18496
	ds_read_b128 v[158:161], v118 offset:46336
	ds_read_b64_tr_b16 v[142:143], v122 offset:5184
	s_waitcnt lgkmcnt(3)
	v_mfma_f32_16x16x32_bf16 v[144:147], v[50:53], v[150:153], v[144:147]
	v_mfma_f32_16x16x32_bf16 v[132:135], v[136:139], v[150:153], v[132:135]
	ds_read_b64_tr_b16 v[152:153], v122 offset:5216
	ds_read_b64_tr_b16 v[150:151], v122 offset:4640
	s_waitcnt lgkmcnt(2)
	v_mfma_f32_16x16x32_bf16 v[144:147], v[140:143], v[154:157], v[144:147]
	s_waitcnt lgkmcnt(0)
	v_mfma_f32_16x16x32_bf16 v[132:135], v[150:153], v[154:157], v[132:135]
	ds_read_b64_tr_b16 v[154:155], v101 offset:64512
	ds_read_b64_tr_b16 v[156:157], v101 offset:65088
	ds_read_b64_tr_b16 v[162:163], v105 offset:4608
	ds_read_b64_tr_b16 v[164:165], v105 offset:5184
	s_waitcnt lgkmcnt(2)
	v_mfma_f32_16x16x32_bf16 v[46:49], v[154:157], v[50:53], v[46:49]
	v_add_u32_e32 v50, 64, v56
	v_cndmask_b32_e64 v50, v129, v50, s[0:1]
	v_add_u32_e32 v50, s30, v50
	v_mfma_f32_16x16x32_bf16 v[42:45], v[154:157], v[136:139], v[42:45]
	s_nop 0
	v_lshl_add_u32 v56, v50, 10, v176
	s_nop 0
	s_waitcnt lgkmcnt(0)
	v_mfma_f32_16x16x32_bf16 v[46:49], v[162:165], v[140:143], v[46:49]
	v_cvt_pk_bf16_f32 v172, v144, v145
	v_cvt_pk_bf16_f32 v173, v146, v147
	s_nop 0
	v_mfma_f32_16x16x32_bf16 v[42:45], v[162:165], v[150:153], v[42:45]
	v_cvt_pk_bf16_f32 v174, v132, v133
	s_nop 2
	v_pk_mul_f32 v[48:49], v[160:161], v[48:49]
	v_pk_mul_f32 v[46:47], v[158:159], v[46:47]
	v_cvt_pk_bf16_f32 v51, v48, v49
	v_cvt_pk_bf16_f32 v50, v46, v47
	v_pk_mul_f32 v[44:45], v[160:161], v[44:45]
	v_pk_mul_f32 v[42:43], v[158:159], v[42:43]
	ds_write_b64 v131, v[50:51] offset:27648
	v_cvt_pk_bf16_f32 v50, v42, v43
	v_cvt_pk_bf16_f32 v51, v44, v45
	ds_write_b64 v119, v[50:51] offset:27648
	ds_read_b128 v[50:53], v113
	v_cvt_pk_bf16_f32 v175, v134, v135
	s_nop 1
	v_permlane16_swap_b32_e32 v172, v174
	v_permlane16_swap_b32_e32 v173, v175
	global_store_dwordx4 v56, v[172:175], s[6:7]
	ds_read_b128 v[132:135], v113 offset:16
	s_waitcnt vmcnt(8)
	v_lshlrev_b32_e32 v136, 16, v38
	s_waitcnt lgkmcnt(1)
	v_exp_f32_e64 v56, -v50
	v_exp_f32_e64 v57, -v51
	v_exp_f32_e32 v50, v50
	v_exp_f32_e32 v51, v51
	v_and_b32_e32 v137, 0xffff0000, v38
	v_pk_mul_f32 v[56:57], v[56:57], v[136:137]
	v_lshlrev_b32_e32 v136, 16, v34
	v_and_b32_e32 v137, 0xffff0000, v34
	v_pk_mul_f32 v[136:137], v[50:51], v[136:137]
	v_lshlrev_b32_e32 v38, 16, v39
	v_cvt_pk_bf16_f32 v34, v136, v137
	v_cvt_pk_bf16_f32 v136, v56, v57
	v_exp_f32_e64 v56, -v52
	v_exp_f32_e64 v57, -v53
	v_exp_f32_e32 v52, v52
	v_exp_f32_e32 v53, v53
	v_and_b32_e32 v39, 0xffff0000, v39
	v_pk_mul_f32 v[38:39], v[56:57], v[38:39]
	v_lshlrev_b32_e32 v56, 16, v35
	v_and_b32_e32 v57, 0xffff0000, v35
	v_pk_mul_f32 v[56:57], v[52:53], v[56:57]
	v_cvt_pk_bf16_f32 v137, v38, v39
	v_cvt_pk_bf16_f32 v35, v56, v57
	s_waitcnt lgkmcnt(0)
	v_exp_f32_e64 v56, -v132
	v_exp_f32_e64 v57, -v133
	v_exp_f32_e32 v38, v132
	v_exp_f32_e32 v39, v133
	v_lshlrev_b32_e32 v138, 16, v40
	v_and_b32_e32 v139, 0xffff0000, v40
	v_pk_mul_f32 v[56:57], v[56:57], v[138:139]
	v_lshlrev_b32_e32 v132, 16, v36
	v_and_b32_e32 v133, 0xffff0000, v36
	v_pk_mul_f32 v[132:133], v[38:39], v[132:133]
	v_cvt_pk_bf16_f32 v138, v56, v57
	v_exp_f32_e64 v56, -v134
	v_exp_f32_e64 v57, -v135
	v_cvt_pk_bf16_f32 v36, v132, v133
	v_lshlrev_b32_e32 v132, 16, v41
	v_and_b32_e32 v133, 0xffff0000, v41
	v_exp_f32_e32 v40, v134
	v_exp_f32_e32 v41, v135
	v_pk_mul_f32 v[56:57], v[56:57], v[132:133]
	v_lshlrev_b32_e32 v132, 16, v37
	v_and_b32_e32 v133, 0xffff0000, v37
	v_pk_mul_f32 v[132:133], v[40:41], v[132:133]
	v_cvt_pk_bf16_f32 v139, v56, v57
	v_cvt_pk_bf16_f32 v37, v132, v133
	ds_write_b128 v111, v[34:37]
	ds_write_b128 v111, v[136:139] offset:55296
	s_and_saveexec_b64 s[26:27], vcc
	s_cbranch_execz .LBB0_232
	ds_write_b128 v126, v[50:53] offset:46080
	ds_write_b128 v126, v[38:41] offset:46096
	s_branch .LBB0_232
